# retention chunk-scan item: all KVT loads issued ahead, stores no longer waited per step
# speedup vs baseline: 1.0090x; 1.0047x over previous
.LBB0_625:
	s_or_b64 exec, exec, s[0:1]
	s_lshl_b32 s0, s76, 12
	s_and_b32 s0, s0, 0x7000
	s_waitcnt vmcnt(0)
	v_add_u32_e32 v8, s0, v176
	v_mov_b32_e32 v9, 0
	s_mul_i32 s0, s14, 17
	s_mov_b32 s1, s15
	s_barrier
	v_lshlrev_b64 v[2:3], 1, v[8:9]
	v_lshlrev_b64 v[4:5], 2, v[8:9]
	s_lshl_b64 s[12:13], s[0:1], 16
	s_add_u32 s6, s54, s12
	s_addc_u32 s7, s55, s13
	s_add_u32 s6, s6, 0x2eec0200
	s_addc_u32 s7, s7, 0
	v_lshl_add_u64 v[10:11], s[6:7], 0, v[2:3]
	s_lshl_b32 s8, s14, 4
	s_mov_b32 s9, s15
	s_lshl_b64 s[12:13], s[8:9], 17
	s_add_u32 s6, s54, s12
	s_addc_u32 s7, s55, s13
	s_add_u32 s6, s6, 0x354c0200
	s_addc_u32 s7, s7, 0
	v_lshl_add_u64 v[12:13], s[6:7], 0, v[4:5]
	s_mov_b64 s[26:27], 0x20000
	s_mov_b64 s[22:23], 0x10000
	global_load_dwordx4 v[140:143], v[12:13], off
	global_load_dwordx4 v[144:147], v[12:13], off offset:16
	v_lshl_add_u64 v[12:13], v[12:13], 0, s[26:27]
	global_load_dwordx4 v[152:155], v[12:13], off
	global_load_dwordx4 v[160:163], v[12:13], off offset:16
	v_lshl_add_u64 v[12:13], v[12:13], 0, s[26:27]
	global_load_dwordx4 v[164:167], v[12:13], off
	global_load_dwordx4 v[168:171], v[12:13], off offset:16
	v_lshl_add_u64 v[12:13], v[12:13], 0, s[26:27]
	global_load_dwordx4 v[172:175], v[12:13], off
	global_load_dwordx4 v[178:181], v[12:13], off offset:16
	v_lshl_add_u64 v[12:13], v[12:13], 0, s[26:27]
	global_load_dwordx4 v[182:185], v[12:13], off
	global_load_dwordx4 v[186:189], v[12:13], off offset:16
	v_lshl_add_u64 v[12:13], v[12:13], 0, s[26:27]
	global_load_dwordx4 v[190:193], v[12:13], off
	global_load_dwordx4 v[194:197], v[12:13], off offset:16
	v_lshl_add_u64 v[12:13], v[12:13], 0, s[26:27]
	global_load_dwordx4 v[198:201], v[12:13], off
	global_load_dwordx4 v[202:205], v[12:13], off offset:16
	v_lshl_add_u64 v[12:13], v[12:13], 0, s[26:27]
	global_load_dwordx4 v[206:209], v[12:13], off
	global_load_dwordx4 v[216:219], v[12:13], off offset:16
	v_lshl_add_u64 v[12:13], v[12:13], 0, s[26:27]
	global_load_dwordx4 v[220:223], v[12:13], off
	global_load_dwordx4 v[224:227], v[12:13], off offset:16
	v_lshl_add_u64 v[12:13], v[12:13], 0, s[26:27]
	global_load_dwordx4 v[238:241], v[12:13], off
	global_load_dwordx4 v[242:245], v[12:13], off offset:16
	v_lshl_add_u64 v[12:13], v[12:13], 0, s[26:27]
	v_mov_b32_e32 v14, 0
	v_mov_b32_e32 v15, 0
	v_mov_b32_e32 v16, 0
	v_mov_b32_e32 v17, 0
	v_mov_b32_e32 v18, 0
	v_mov_b32_e32 v19, 0
	v_mov_b32_e32 v20, 0
	v_mov_b32_e32 v21, 0
	v_cvt_pk_bf16_f32 v6, v14, v15
	v_cvt_pk_bf16_f32 v7, v18, v19
	v_cvt_pk_bf16_f32 v8, v16, v17
	v_cvt_pk_bf16_f32 v9, v20, v21
	s_nop 1
	global_store_dwordx4 v[10:11], v[6:9], off sc1
	s_nop 1
	v_lshl_add_u64 v[10:11], v[10:11], 0, s[22:23]
	s_waitcnt vmcnt(19)
	v_pk_fma_f32 v[14:15], v[150:151], v[14:15], v[140:141]
	v_pk_fma_f32 v[18:19], v[150:151], v[18:19], v[142:143]
	v_pk_fma_f32 v[16:17], v[150:151], v[16:17], v[144:145]
	v_pk_fma_f32 v[20:21], v[150:151], v[20:21], v[146:147]
	global_load_dwordx4 v[140:143], v[12:13], off
	global_load_dwordx4 v[144:147], v[12:13], off offset:16
	v_lshl_add_u64 v[12:13], v[12:13], 0, s[26:27]
	v_cvt_pk_bf16_f32 v6, v14, v15
	v_cvt_pk_bf16_f32 v7, v18, v19
	v_cvt_pk_bf16_f32 v8, v16, v17
	v_cvt_pk_bf16_f32 v9, v20, v21
	s_nop 1
	global_store_dwordx4 v[10:11], v[6:9], off sc1
	s_nop 1
	v_lshl_add_u64 v[10:11], v[10:11], 0, s[22:23]
	s_waitcnt vmcnt(20)
	v_pk_fma_f32 v[14:15], v[150:151], v[14:15], v[152:153]
	v_pk_fma_f32 v[18:19], v[150:151], v[18:19], v[154:155]
	v_pk_fma_f32 v[16:17], v[150:151], v[16:17], v[160:161]
	v_pk_fma_f32 v[20:21], v[150:151], v[20:21], v[162:163]
	global_load_dwordx4 v[152:155], v[12:13], off
	global_load_dwordx4 v[160:163], v[12:13], off offset:16
	v_lshl_add_u64 v[12:13], v[12:13], 0, s[26:27]
	v_cvt_pk_bf16_f32 v6, v14, v15
	v_cvt_pk_bf16_f32 v7, v18, v19
	v_cvt_pk_bf16_f32 v8, v16, v17
	v_cvt_pk_bf16_f32 v9, v20, v21
	s_nop 1
	global_store_dwordx4 v[10:11], v[6:9], off sc1
	s_nop 1
	v_lshl_add_u64 v[10:11], v[10:11], 0, s[22:23]
	s_waitcnt vmcnt(21)
	v_pk_fma_f32 v[14:15], v[150:151], v[14:15], v[164:165]
	v_pk_fma_f32 v[18:19], v[150:151], v[18:19], v[166:167]
	v_pk_fma_f32 v[16:17], v[150:151], v[16:17], v[168:169]
	v_pk_fma_f32 v[20:21], v[150:151], v[20:21], v[170:171]
	global_load_dwordx4 v[164:167], v[12:13], off
	global_load_dwordx4 v[168:171], v[12:13], off offset:16
	v_lshl_add_u64 v[12:13], v[12:13], 0, s[26:27]
	v_cvt_pk_bf16_f32 v6, v14, v15
	v_cvt_pk_bf16_f32 v7, v18, v19
	v_cvt_pk_bf16_f32 v8, v16, v17
	v_cvt_pk_bf16_f32 v9, v20, v21
	s_nop 1
	global_store_dwordx4 v[10:11], v[6:9], off sc1
	s_nop 1
	v_lshl_add_u64 v[10:11], v[10:11], 0, s[22:23]
	s_waitcnt vmcnt(22)
	v_pk_fma_f32 v[14:15], v[150:151], v[14:15], v[172:173]
	v_pk_fma_f32 v[18:19], v[150:151], v[18:19], v[174:175]
	v_pk_fma_f32 v[16:17], v[150:151], v[16:17], v[178:179]
	v_pk_fma_f32 v[20:21], v[150:151], v[20:21], v[180:181]
	global_load_dwordx4 v[172:175], v[12:13], off
	global_load_dwordx4 v[178:181], v[12:13], off offset:16
	v_lshl_add_u64 v[12:13], v[12:13], 0, s[26:27]
	v_cvt_pk_bf16_f32 v6, v14, v15
	v_cvt_pk_bf16_f32 v7, v18, v19
	v_cvt_pk_bf16_f32 v8, v16, v17
	v_cvt_pk_bf16_f32 v9, v20, v21
	s_nop 1
	global_store_dwordx4 v[10:11], v[6:9], off sc1
	s_nop 1
	v_lshl_add_u64 v[10:11], v[10:11], 0, s[22:23]
	s_waitcnt vmcnt(23)
	v_pk_fma_f32 v[14:15], v[150:151], v[14:15], v[182:183]
	v_pk_fma_f32 v[18:19], v[150:151], v[18:19], v[184:185]
	v_pk_fma_f32 v[16:17], v[150:151], v[16:17], v[186:187]
	v_pk_fma_f32 v[20:21], v[150:151], v[20:21], v[188:189]
	global_load_dwordx4 v[182:185], v[12:13], off
	global_load_dwordx4 v[186:189], v[12:13], off offset:16
	v_lshl_add_u64 v[12:13], v[12:13], 0, s[26:27]
	v_cvt_pk_bf16_f32 v6, v14, v15
	v_cvt_pk_bf16_f32 v7, v18, v19
	v_cvt_pk_bf16_f32 v8, v16, v17
	v_cvt_pk_bf16_f32 v9, v20, v21
	s_nop 1
	global_store_dwordx4 v[10:11], v[6:9], off sc1
	s_nop 1
	v_lshl_add_u64 v[10:11], v[10:11], 0, s[22:23]
	s_waitcnt vmcnt(24)
	v_pk_fma_f32 v[14:15], v[150:151], v[14:15], v[190:191]
	v_pk_fma_f32 v[18:19], v[150:151], v[18:19], v[192:193]
	v_pk_fma_f32 v[16:17], v[150:151], v[16:17], v[194:195]
	v_pk_fma_f32 v[20:21], v[150:151], v[20:21], v[196:197]
	global_load_dwordx4 v[190:193], v[12:13], off
	global_load_dwordx4 v[194:197], v[12:13], off offset:16
	v_lshl_add_u64 v[12:13], v[12:13], 0, s[26:27]
	v_cvt_pk_bf16_f32 v6, v14, v15
	v_cvt_pk_bf16_f32 v7, v18, v19
	v_cvt_pk_bf16_f32 v8, v16, v17
	v_cvt_pk_bf16_f32 v9, v20, v21
	s_nop 1
	global_store_dwordx4 v[10:11], v[6:9], off sc1
	s_nop 1
	v_lshl_add_u64 v[10:11], v[10:11], 0, s[22:23]
	s_waitcnt vmcnt(25)
	v_pk_fma_f32 v[14:15], v[150:151], v[14:15], v[198:199]
	v_pk_fma_f32 v[18:19], v[150:151], v[18:19], v[200:201]
	v_pk_fma_f32 v[16:17], v[150:151], v[16:17], v[202:203]
	v_pk_fma_f32 v[20:21], v[150:151], v[20:21], v[204:205]
	v_cvt_pk_bf16_f32 v6, v14, v15
	v_cvt_pk_bf16_f32 v7, v18, v19
	v_cvt_pk_bf16_f32 v8, v16, v17
	v_cvt_pk_bf16_f32 v9, v20, v21
	s_nop 1
	global_store_dwordx4 v[10:11], v[6:9], off sc1
	s_nop 1
	v_lshl_add_u64 v[10:11], v[10:11], 0, s[22:23]
	s_waitcnt vmcnt(24)
	v_pk_fma_f32 v[14:15], v[150:151], v[14:15], v[206:207]
	v_pk_fma_f32 v[18:19], v[150:151], v[18:19], v[208:209]
	v_pk_fma_f32 v[16:17], v[150:151], v[16:17], v[216:217]
	v_pk_fma_f32 v[20:21], v[150:151], v[20:21], v[218:219]
	v_cvt_pk_bf16_f32 v6, v14, v15
	v_cvt_pk_bf16_f32 v7, v18, v19
	v_cvt_pk_bf16_f32 v8, v16, v17
	v_cvt_pk_bf16_f32 v9, v20, v21
	s_nop 1
	global_store_dwordx4 v[10:11], v[6:9], off sc1
	s_nop 1
	v_lshl_add_u64 v[10:11], v[10:11], 0, s[22:23]
	s_waitcnt vmcnt(23)
	v_pk_fma_f32 v[14:15], v[150:151], v[14:15], v[220:221]
	v_pk_fma_f32 v[18:19], v[150:151], v[18:19], v[222:223]
	v_pk_fma_f32 v[16:17], v[150:151], v[16:17], v[224:225]
	v_pk_fma_f32 v[20:21], v[150:151], v[20:21], v[226:227]
	v_cvt_pk_bf16_f32 v6, v14, v15
	v_cvt_pk_bf16_f32 v7, v18, v19
	v_cvt_pk_bf16_f32 v8, v16, v17
	v_cvt_pk_bf16_f32 v9, v20, v21
	s_nop 1
	global_store_dwordx4 v[10:11], v[6:9], off sc1
	s_nop 1
	v_lshl_add_u64 v[10:11], v[10:11], 0, s[22:23]
	s_waitcnt vmcnt(22)
	v_pk_fma_f32 v[14:15], v[150:151], v[14:15], v[238:239]
	v_pk_fma_f32 v[18:19], v[150:151], v[18:19], v[240:241]
	v_pk_fma_f32 v[16:17], v[150:151], v[16:17], v[242:243]
	v_pk_fma_f32 v[20:21], v[150:151], v[20:21], v[244:245]
	v_cvt_pk_bf16_f32 v6, v14, v15
	v_cvt_pk_bf16_f32 v7, v18, v19
	v_cvt_pk_bf16_f32 v8, v16, v17
	v_cvt_pk_bf16_f32 v9, v20, v21
	s_nop 1
	global_store_dwordx4 v[10:11], v[6:9], off sc1
	s_nop 1
	v_lshl_add_u64 v[10:11], v[10:11], 0, s[22:23]
	s_waitcnt vmcnt(20)
	v_pk_fma_f32 v[14:15], v[150:151], v[14:15], v[140:141]
	v_pk_fma_f32 v[18:19], v[150:151], v[18:19], v[142:143]
	v_pk_fma_f32 v[16:17], v[150:151], v[16:17], v[144:145]
	v_pk_fma_f32 v[20:21], v[150:151], v[20:21], v[146:147]
	v_cvt_pk_bf16_f32 v6, v14, v15
	v_cvt_pk_bf16_f32 v7, v18, v19
	v_cvt_pk_bf16_f32 v8, v16, v17
	v_cvt_pk_bf16_f32 v9, v20, v21
	s_nop 1
	global_store_dwordx4 v[10:11], v[6:9], off sc1
	s_nop 1
	v_lshl_add_u64 v[10:11], v[10:11], 0, s[22:23]
	s_waitcnt vmcnt(18)
	v_pk_fma_f32 v[14:15], v[150:151], v[14:15], v[152:153]
	v_pk_fma_f32 v[18:19], v[150:151], v[18:19], v[154:155]
	v_pk_fma_f32 v[16:17], v[150:151], v[16:17], v[160:161]
	v_pk_fma_f32 v[20:21], v[150:151], v[20:21], v[162:163]
	v_cvt_pk_bf16_f32 v6, v14, v15
	v_cvt_pk_bf16_f32 v7, v18, v19
	v_cvt_pk_bf16_f32 v8, v16, v17
	v_cvt_pk_bf16_f32 v9, v20, v21
	s_nop 1
	global_store_dwordx4 v[10:11], v[6:9], off sc1
	s_nop 1
	v_lshl_add_u64 v[10:11], v[10:11], 0, s[22:23]
	s_waitcnt vmcnt(16)
	v_pk_fma_f32 v[14:15], v[150:151], v[14:15], v[164:165]
	v_pk_fma_f32 v[18:19], v[150:151], v[18:19], v[166:167]
	v_pk_fma_f32 v[16:17], v[150:151], v[16:17], v[168:169]
	v_pk_fma_f32 v[20:21], v[150:151], v[20:21], v[170:171]
	v_cvt_pk_bf16_f32 v6, v14, v15
	v_cvt_pk_bf16_f32 v7, v18, v19
	v_cvt_pk_bf16_f32 v8, v16, v17
	v_cvt_pk_bf16_f32 v9, v20, v21
	s_nop 1
	global_store_dwordx4 v[10:11], v[6:9], off sc1
	s_nop 1
	v_lshl_add_u64 v[10:11], v[10:11], 0, s[22:23]
	s_waitcnt vmcnt(14)
	v_pk_fma_f32 v[14:15], v[150:151], v[14:15], v[172:173]
	v_pk_fma_f32 v[18:19], v[150:151], v[18:19], v[174:175]
	v_pk_fma_f32 v[16:17], v[150:151], v[16:17], v[178:179]
	v_pk_fma_f32 v[20:21], v[150:151], v[20:21], v[180:181]
	v_cvt_pk_bf16_f32 v6, v14, v15
	v_cvt_pk_bf16_f32 v7, v18, v19
	v_cvt_pk_bf16_f32 v8, v16, v17
	v_cvt_pk_bf16_f32 v9, v20, v21
	s_nop 1
	global_store_dwordx4 v[10:11], v[6:9], off sc1
	s_nop 1
	v_lshl_add_u64 v[10:11], v[10:11], 0, s[22:23]
	s_waitcnt vmcnt(12)
	v_pk_fma_f32 v[14:15], v[150:151], v[14:15], v[182:183]
	v_pk_fma_f32 v[18:19], v[150:151], v[18:19], v[184:185]
	v_pk_fma_f32 v[16:17], v[150:151], v[16:17], v[186:187]
	v_pk_fma_f32 v[20:21], v[150:151], v[20:21], v[188:189]
	v_cvt_pk_bf16_f32 v6, v14, v15
	v_cvt_pk_bf16_f32 v7, v18, v19
	v_cvt_pk_bf16_f32 v8, v16, v17
	v_cvt_pk_bf16_f32 v9, v20, v21
	s_nop 1
	global_store_dwordx4 v[10:11], v[6:9], off sc1
	s_nop 1
	v_lshl_add_u64 v[10:11], v[10:11], 0, s[22:23]
	s_waitcnt vmcnt(10)
	v_pk_fma_f32 v[14:15], v[150:151], v[14:15], v[190:191]
	v_pk_fma_f32 v[18:19], v[150:151], v[18:19], v[192:193]
	v_pk_fma_f32 v[16:17], v[150:151], v[16:17], v[194:195]
	v_pk_fma_f32 v[20:21], v[150:151], v[20:21], v[196:197]
	v_cvt_pk_bf16_f32 v6, v14, v15
	v_cvt_pk_bf16_f32 v7, v18, v19
	v_cvt_pk_bf16_f32 v8, v16, v17
	v_cvt_pk_bf16_f32 v9, v20, v21
	s_nop 1
	global_store_dwordx4 v[10:11], v[6:9], off sc1
	s_nop 1
	s_waitcnt vmcnt(0)
	s_barrier
	s_mov_b64 s[0:1], exec
	v_readlane_b32 s6, v253, 0
	v_readlane_b32 s7, v253, 1
	s_and_b64 s[6:7], s[0:1], s[6:7]
	s_xor_b64 s[0:1], s[6:7], s[0:1]
	s_mov_b64 exec, s[6:7]
	s_cbranch_execz .LBB0_629
	s_mov_b64 s[6:7], exec
	v_mbcnt_lo_u32_b32 v0, s6, 0
	v_mbcnt_hi_u32_b32 v0, s7, v0
	v_cmp_eq_u32_e32 vcc, 0, v0
	s_and_saveexec_b64 s[8:9], vcc
	s_xor_b64 s[8:9], exec, s[8:9]
	s_cbranch_execz .LBB0_628
	s_lshl_b64 s[12:13], s[14:15], 2
	v_readlane_b32 s14, v255, 20
	s_add_u32 s12, s14, s12
	v_readlane_b32 s14, v255, 21
	s_addc_u32 s13, s14, s13
	s_bcnt1_i32_b64 s6, s[6:7]
	v_mov_b32_e32 v0, s6
	global_atomic_add v1, v0, s[12:13]
